# mixer-A: waves 4-7 run the tile loop rotated by one segment (PV2 of previous tile first), third V ring slot
# baseline (speedup 1.0000x reference)
.LBB0_406:
	s_lshl_b32 s2, s6, 4
	v_readlane_b32 s3, v254, 17
	s_add_i32 s2, s3, s2
	s_ashr_i32 s4, s2, 3
	v_mbcnt_lo_u32_b32 v9, -1, 0
	v_mbcnt_hi_u32_b32 v9, -1, v9
	s_ashr_i32 s5, s4, 31
	v_ashrrev_i32_e32 v0, 3, v9
	v_add_u32_e32 v1, s36, v0
	s_lshl_b64 s[2:3], s[4:5], 12
	v_lshrrev_b32_e32 v1, 1, v1
	v_xor_b32_e32 v1, v1, v9
	s_add_i32 s5, s2, s36
	v_lshlrev_b32_e32 v1, 3, v1
	v_add_lshl_u32 v11, s5, v0, 10
	v_readlane_b32 s5, v254, 4
	v_and_b32_e32 v10, 56, v1
	v_ashrrev_i32_e32 v1, 4, v9
	s_add_i32 s5, s5, s2
	v_add_lshl_u32 v13, s5, v1, 10
	v_readlane_b32 s5, v254, 6
	v_and_b32_e32 v2, 15, v9
	v_lshlrev_b32_e32 v3, 2, v1
	s_add_u32 s2, s2, s5
	v_readlane_b32 s5, v254, 7
	v_lshrrev_b32_e32 v1, 4, v9
	v_bitop3_b32 v2, v3, v2, 12 bitop3:0x6c
	s_addc_u32 s3, s3, s5
	v_xor_b32_e32 v4, v1, v9
	v_ashrrev_i32_e32 v1, 31, v0
	v_lshlrev_b32_e32 v12, 3, v2
	v_lshl_add_u64 v[2:3], s[2:3], 0, v[0:1]
	v_lshlrev_b32_e32 v1, 4, v4
	v_and_b32_e32 v160, 0x70, v1
	v_add_u32_e32 v1, 64, v9
	v_ashrrev_i32_e32 v4, 3, v1
	v_lshrrev_b32_e32 v1, 4, v1
	v_ashrrev_i32_e32 v5, 31, v4
	v_xor_b32_e32 v1, v1, v9
	v_lshl_add_u64 v[4:5], s[2:3], 0, v[4:5]
	v_lshlrev_b64 v[4:5], 11, v[4:5]
	v_lshlrev_b32_e32 v1, 4, v1
	v_lshl_add_u64 v[4:5], s[92:93], 0, v[4:5]
	v_and_b32_e32 v6, 0x70, v1
	v_mov_b32_e32 v7, v161
	v_add_u32_e32 v1, 0x80, v9
	v_lshl_add_u64 v[4:5], v[4:5], 0, v[6:7]
	v_ashrrev_i32_e32 v6, 3, v1
	v_add_u32_e32 v1, 0xc0, v9
	v_lshlrev_b64 v[2:3], 11, v[2:3]
	v_readlane_b32 s5, v254, 5
	v_ashrrev_i32_e32 v7, 31, v6
	v_ashrrev_i32_e32 v8, 3, v1
	v_lshrrev_b32_e32 v1, 4, v1
	v_lshl_add_u64 v[2:3], s[92:93], 0, v[2:3]
	s_add_i32 s5, s5, 0
	v_lshl_add_u64 v[6:7], s[2:3], 0, v[6:7]
	v_xor_b32_e32 v1, v1, v9
	v_ashrrev_i32_e32 v9, 31, v8
	v_lshl_add_u64 v[2:3], v[2:3], 0, v[160:161]
	s_add_i32 s7, s5, 0x10000
	s_mov_b32 s8, m0
	s_mov_b32 m0, s7
	s_nop 0
	global_load_lds_dwordx4 v[2:3], off
	s_mov_b32 m0, s8
	v_lshlrev_b64 v[6:7], 11, v[6:7]
	v_lshl_add_u64 v[8:9], s[2:3], 0, v[8:9]
	s_add_i32 s7, s5, 0x10400
	s_mov_b32 s8, m0
	s_mov_b32 m0, s7
	s_nop 0
	global_load_lds_dwordx4 v[4:5], off
	s_mov_b32 m0, s8
	v_lshl_add_u64 v[6:7], s[92:93], 0, v[6:7]
	v_lshlrev_b64 v[8:9], 11, v[8:9]
	v_lshlrev_b32_e32 v1, 4, v1
	v_lshl_add_u64 v[6:7], v[6:7], 0, v[160:161]
	s_add_i32 s7, s5, 0x10800
	s_mov_b32 s8, m0
	s_mov_b32 m0, s7
	s_nop 0
	global_load_lds_dwordx4 v[6:7], off
	s_mov_b32 m0, s8
	v_lshl_add_u64 v[8:9], s[92:93], 0, v[8:9]
	v_and_b32_e32 v160, 0x70, v1
	v_lshl_add_u64 v[8:9], v[8:9], 0, v[160:161]
	s_add_i32 s7, s5, 0x10c00
	s_mov_b32 s8, m0
	s_mov_b32 m0, s7
	s_nop 0
	global_load_lds_dwordx4 v[8:9], off
	s_mov_b32 m0, s8
	v_lshl_add_u64 v[2:3], v[2:3], 0, s[38:39]
	s_add_i32 s7, s5, 0x11000
	s_mov_b32 s8, m0
	s_mov_b32 m0, s7
	s_nop 0
	global_load_lds_dwordx4 v[2:3], off
	s_mov_b32 m0, s8
	v_lshl_add_u64 v[2:3], v[4:5], 0, s[38:39]
	s_add_i32 s7, s5, 0x11400
	s_mov_b32 s8, m0
	s_mov_b32 m0, s7
	s_nop 0
	global_load_lds_dwordx4 v[2:3], off
	s_mov_b32 m0, s8
	v_lshl_add_u64 v[2:3], v[6:7], 0, s[38:39]
	s_add_i32 s7, s5, 0x11800
	s_mov_b32 s8, m0
	s_mov_b32 m0, s7
	s_nop 0
	global_load_lds_dwordx4 v[2:3], off
	s_mov_b32 m0, s8
	v_lshl_add_u64 v[2:3], v[8:9], 0, s[38:39]
	s_add_i32 s5, s5, 0x11c00
	s_mov_b32 s7, m0
	s_mov_b32 m0, s5
	s_nop 0
	global_load_lds_dwordx4 v[2:3], off
	s_mov_b32 m0, s7
	v_or3_b32 v160, v10, v11, s40
	v_lshl_add_u64 v[4:5], v[160:161], 1, s[66:67]
	s_mov_b32 s5, m0
	s_mov_b32 m0, s49
	s_nop 0
	global_load_lds_dwordx4 v[4:5], off
	s_mov_b32 m0, s5
	v_or3_b32 v2, v12, v13, s40
	v_lshl_add_u64 v[4:5], v[4:5], 0, s[38:39]
	s_mov_b32 s5, m0
	s_mov_b32 m0, s33
	s_nop 0
	global_load_lds_dwordx4 v[4:5], off
	s_mov_b32 m0, s5
	v_mov_b32_e32 v3, v161
	v_lshl_add_u64 v[4:5], v[2:3], 1, s[68:69]
	s_mov_b32 s5, m0
	s_mov_b32 m0, s54
	s_nop 0
	global_load_lds_dwordx4 v[4:5], off
	s_mov_b32 m0, s5
	v_add_u32_e32 v160, 0x8000, v2
	v_lshl_add_u64 v[2:3], v[160:161], 1, s[68:69]
	s_mov_b32 s5, m0
	s_mov_b32 m0, s47
	s_nop 0
	global_load_lds_dwordx4 v[2:3], off
	s_mov_b32 m0, s5
	s_lshl_b32 s4, s4, 22
	v_readlane_b32 s5, v255, 1
	s_add_i32 s4, s5, s4
	v_lshlrev_b32_e32 v0, 10, v0
	v_or_b32_e32 v1, s40, v13
	v_add3_u32 v202, s4, v0, v10
	v_mov_b32_e32 v0, 0
	v_add_u32_e32 v201, v1, v12
	s_mov_b32 s4, 0
	s_mov_b32 s5, 0
	v_mov_b32_e32 v1, v0
	v_mov_b32_e32 v2, v0
	v_mov_b32_e32 v3, v0
	v_mov_b32_e32 v4, v0
	v_mov_b32_e32 v5, v0
	v_mov_b32_e32 v6, v0
	v_mov_b32_e32 v7, v0
	v_mov_b32_e32 v8, v0
	v_mov_b32_e32 v9, v0
	v_mov_b32_e32 v10, v0
	v_mov_b32_e32 v11, v0
	v_mov_b32_e32 v12, v0
	v_mov_b32_e32 v13, v0
	v_mov_b32_e32 v14, v0
	v_mov_b32_e32 v15, v0
	v_mov_b32_e32 v16, v0
	v_mov_b32_e32 v17, v0
	v_mov_b32_e32 v18, v0
	v_mov_b32_e32 v19, v0
	v_mov_b32_e32 v20, v0
	v_mov_b32_e32 v21, v0
	v_mov_b32_e32 v22, v0
	v_mov_b32_e32 v23, v0
	v_mov_b32_e32 v24, v0
	v_mov_b32_e32 v25, v0
	v_mov_b32_e32 v26, v0
	v_mov_b32_e32 v27, v0
	v_mov_b32_e32 v28, v0
	v_mov_b32_e32 v29, v0
	v_mov_b32_e32 v30, v0
	v_mov_b32_e32 v31, v0
	v_mov_b32_e32 v32, v0
	v_mov_b32_e32 v33, v0
	v_mov_b32_e32 v34, v0
	v_mov_b32_e32 v35, v0
	v_mov_b32_e32 v36, v0
	v_mov_b32_e32 v37, v0
	v_mov_b32_e32 v38, v0
	v_mov_b32_e32 v39, v0
	v_mov_b32_e32 v40, v0
	v_mov_b32_e32 v41, v0
	v_mov_b32_e32 v42, v0
	v_mov_b32_e32 v43, v0
	v_mov_b32_e32 v44, v0
	v_mov_b32_e32 v45, v0
	v_mov_b32_e32 v46, v0
	v_mov_b32_e32 v47, v0
	v_mov_b32_e32 v48, v0
	v_mov_b32_e32 v49, v0
	v_mov_b32_e32 v50, v0
	v_mov_b32_e32 v51, v0
	v_mov_b32_e32 v52, v0
	v_mov_b32_e32 v53, v0
	v_mov_b32_e32 v54, v0
	v_mov_b32_e32 v55, v0
	v_mov_b32_e32 v56, v0
	v_mov_b32_e32 v57, v0
	v_mov_b32_e32 v58, v0
	v_mov_b32_e32 v59, v0
	v_mov_b32_e32 v60, v0
	v_mov_b32_e32 v61, v0
	v_mov_b32_e32 v62, v0
	v_mov_b32_e32 v63, v0
	v_mov_b32_e32 v64, v0
	v_mov_b32_e32 v65, v0
	v_mov_b32_e32 v66, v0
	v_mov_b32_e32 v67, v0
	v_mov_b32_e32 v68, v0
	v_mov_b32_e32 v69, v0
	v_mov_b32_e32 v70, v0
	v_mov_b32_e32 v71, v0
	v_mov_b32_e32 v72, v0
	v_mov_b32_e32 v73, v0
	v_mov_b32_e32 v74, v0
	v_mov_b32_e32 v75, v0
	v_mov_b32_e32 v76, v0
	v_mov_b32_e32 v77, v0
	v_mov_b32_e32 v78, v0
	v_mov_b32_e32 v79, v0
	v_mov_b32_e32 v80, v0
	v_mov_b32_e32 v81, v0
	v_mov_b32_e32 v82, v0
	v_mov_b32_e32 v83, v0
	v_mov_b32_e32 v84, v0
	v_mov_b32_e32 v85, v0
	v_mov_b32_e32 v86, v0
	v_mov_b32_e32 v87, v0
	v_mov_b32_e32 v88, v0
	v_mov_b32_e32 v89, v0
	v_mov_b32_e32 v90, v0
	v_mov_b32_e32 v91, v0
	v_mov_b32_e32 v92, v0
	v_mov_b32_e32 v93, v0
	v_mov_b32_e32 v94, v0
	v_mov_b32_e32 v95, v0
	v_mov_b32_e32 v96, v0
	v_mov_b32_e32 v97, v0
	v_mov_b32_e32 v98, v0
	v_mov_b32_e32 v99, v0
	v_mov_b32_e32 v100, v0
	v_mov_b32_e32 v101, v0
	v_mov_b32_e32 v102, v0
	v_mov_b32_e32 v103, v0
	v_mov_b32_e32 v104, v0
	v_mov_b32_e32 v105, v0
	v_mov_b32_e32 v106, v0
	v_mov_b32_e32 v107, v0
	v_mov_b32_e32 v108, v0
	v_mov_b32_e32 v109, v0
	v_mov_b32_e32 v110, v0
	v_mov_b32_e32 v111, v0
	v_mov_b32_e32 v112, v0
	v_mov_b32_e32 v113, v0
	v_mov_b32_e32 v114, v0
	v_mov_b32_e32 v115, v0
	v_mov_b32_e32 v116, v0
	v_mov_b32_e32 v117, v0
	v_mov_b32_e32 v118, v0
	v_mov_b32_e32 v119, v0
	v_mov_b32_e32 v120, v0
	v_mov_b32_e32 v121, v0
	v_mov_b32_e32 v122, v0
	v_mov_b32_e32 v123, v0
	v_mov_b32_e32 v124, v0
	v_mov_b32_e32 v125, v0
	v_mov_b32_e32 v126, v0
	v_mov_b32_e32 v127, v0
	v_mov_b32_e32 v166, v0
	v_mov_b32_e32 v167, v0
	s_waitcnt vmcnt(0)
	s_mov_b32 s99, 0
	s_movk_i32 s100, 0x4000
	s_mov_b32 s101, 0x18c00
	v_readlane_b32 s98, v253, 39
	s_cmpk_ge_u32 s98, 0x100
	s_cbranch_scc0 .Lattn_prio_skip_a
	s_setprio 1
	s_barrier
	s_branch .Lattn_late_entry

.LBB0_407:
	v_mbcnt_lo_u32_b32 v128, -1, 0
	v_mbcnt_hi_u32_b32 v128, -1, v128
	s_add_i32 s7, s7, 0
	v_bfe_u32 v129, v128, 2, 2
	v_lshrrev_b32_e32 v130, 3, v128
	v_bfe_u32 v132, v128, 1, 1
	v_and_or_b32 v131, v130, s64, v129
	v_and_or_b32 v130, v130, 2, v132
	v_lshlrev_b32_e32 v128, 3, v128
	v_lshlrev_b32_e32 v131, 8, v131
	v_lshlrev_b32_e32 v130, 4, v130
	v_and_b32_e32 v128, 8, v128
	v_or3_b32 v160, v130, v131, v128
	v_lshlrev_b32_e32 v162, 6, v129
	v_mbcnt_lo_u32_b32 v128, -1, 0
	v_mbcnt_hi_u32_b32 v128, -1, v128
	v_or_b32_e32 v163, v160, v162
	v_ashrrev_i32_e32 v129, 5, v128
	v_lshlrev_b32_e32 v130, 7, v128
	v_lshrrev_b32_e32 v133, 1, v128
	v_and_b32_e32 v132, 0xf80, v130
	v_bitop3_b32 v128, v133, v129, 7 bitop3:0x6c
	v_lshl_add_u32 v134, v128, 4, v132
	v_add_u32_e32 v128, 2, v129
	v_bitop3_b32 v128, v128, v133, 7 bitop3:0x78
	v_lshl_add_u32 v136, v128, 4, v132
	v_add_u32_e32 v128, 4, v129
	v_bitop3_b32 v128, v128, v133, 7 bitop3:0x78
	v_add_u32_e32 v207, s7, v134
	v_lshl_add_u32 v168, v128, 4, v132
	v_add_u32_e32 v135, 6, v129
	ds_read_b128 v[128:131], v207
	v_bitop3_b32 v133, v135, v133, 7 bitop3:0x78
	v_add_u32_e32 v224, s48, v134
	v_add_u32_e32 v225, s7, v136
	v_lshl_add_u32 v169, v133, 4, v132
	ds_read_b128 v[132:135], v224
	v_add_u32_e32 v226, s48, v136
	ds_read_b128 v[136:139], v225
	ds_read_b128 v[140:143], v226
	v_bitop3_b32 v203, v160, s37, v162 bitop3:0x36
	v_bitop3_b32 v206, v160, s41, v162 bitop3:0x36
	s_waitcnt lgkmcnt(2)
	v_mfma_f32_32x32x16_bf16 v[144:159], v[128:131], v[132:135], 0
	v_add_u32_e32 v227, s7, v168
	v_add_u32_e32 v228, s48, v168
	ds_read_b128 v[128:131], v227
	ds_read_b128 v[132:135], v228
	s_waitcnt lgkmcnt(2)
	v_mfma_f32_32x32x16_bf16 v[144:159], v[136:139], v[140:143], v[144:159]
	v_add_u32_e32 v230, s7, v169
	v_add_u32_e32 v232, s48, v169
	ds_read_b128 v[136:139], v230
	ds_read_b128 v[140:143], v232
	s_waitcnt lgkmcnt(2)
	v_mfma_f32_32x32x16_bf16 v[144:159], v[128:131], v[132:135], v[144:159]
	ds_read_b128 v[128:131], v207 offset:8192
	ds_read_b128 v[132:135], v224 offset:4096
	s_waitcnt lgkmcnt(2)
	v_mfma_f32_32x32x16_bf16 v[144:159], v[136:139], v[140:143], v[144:159]
	ds_read_b128 v[178:181], v225 offset:8192
	ds_read_b128 v[182:185], v226 offset:4096
	s_waitcnt lgkmcnt(2)
	v_mfma_f32_32x32x16_bf16 v[128:143], v[128:131], v[132:135], 0
	s_nop 7
	v_exp_f32_e32 v173, v144
	v_exp_f32_e32 v169, v145
	v_exp_f32_e32 v177, v146
	v_exp_f32_e32 v171, v147
	ds_read_b128 v[144:147], v227 offset:8192
	ds_read_b128 v[190:193], v228 offset:4096
	s_waitcnt lgkmcnt(2)
	v_mfma_f32_32x32x16_bf16 v[128:143], v[178:181], v[182:185], v[128:143]
	v_exp_f32_e32 v183, v148
	v_exp_f32_e32 v175, v149
	v_exp_f32_e32 v189, v150
	v_exp_f32_e32 v179, v151
	ds_read_b128 v[148:151], v230 offset:8192
	ds_read_b128 v[196:199], v232 offset:4096
	s_waitcnt lgkmcnt(2)
	v_mfma_f32_32x32x16_bf16 v[128:143], v[144:147], v[190:193], v[128:143]
	v_exp_f32_e32 v193, v152
	v_exp_f32_e32 v181, v153
	v_exp_f32_e32 v195, v154
	v_exp_f32_e32 v187, v155
	s_waitcnt lgkmcnt(0)
	v_mfma_f32_32x32x16_bf16 v[128:143], v[148:151], v[196:199], v[128:143]
	v_exp_f32_e32 v197, v156
	v_exp_f32_e32 v185, v157
	v_exp_f32_e32 v199, v158
	v_exp_f32_e32 v191, v159
	s_cmp_eq_u32 s4, 0x3f0000
	s_cbranch_scc1 .Lattn_nodma_a
	v_mov_b32_e32 v213, 0
	v_add_u32_e32 v212, s4, v202
	s_xor_b32 s8, s7, 0x4000
	v_lshl_add_u64 v[208:209], v[212:213], 1, s[66:67]
	s_add_i32 s9, s49, s8
	s_mov_b32 s10, m0
	s_mov_b32 m0, s9
	s_nop 0
	global_load_lds_dwordx4 v[208:209], off
	s_mov_b32 m0, s10
	v_add_u32_e32 v210, s4, v201
	v_lshl_add_u64 v[208:209], v[208:209], 0, s[38:39]
	s_add_i32 s9, s33, s8
	s_mov_b32 s10, m0
	s_mov_b32 m0, s9
	s_nop 0
	global_load_lds_dwordx4 v[208:209], off
	s_mov_b32 m0, s10
	v_add_u32_e32 v212, 0x10000, v210
	v_lshl_add_u64 v[208:209], v[212:213], 1, s[68:69]
	s_add_i32 s9, s54, s100
	s_mov_b32 s10, m0
	s_mov_b32 m0, s9
	s_nop 0
	global_load_lds_dwordx4 v[208:209], off
	s_mov_b32 m0, s10
	v_add_u32_e32 v212, 0x18000, v210
	v_lshl_add_u64 v[208:209], v[212:213], 1, s[68:69]
	s_add_i32 s8, s47, s100
	s_mov_b32 s9, m0
	s_mov_b32 m0, s8
	s_nop 0
	global_load_lds_dwordx4 v[208:209], off
	s_mov_b32 m0, s9
	s_branch .Lattn_dma_done_a

.Lattn_dma_done_a:
	v_exp_f32_e32 v172, v128
	v_exp_f32_e32 v170, v129
	v_exp_f32_e32 v176, v130
	v_exp_f32_e32 v168, v131
	v_exp_f32_e32 v182, v132
	v_exp_f32_e32 v178, v133
	v_exp_f32_e32 v188, v134
	v_exp_f32_e32 v174, v135
	v_exp_f32_e32 v192, v136
	v_exp_f32_e32 v186, v137
	v_exp_f32_e32 v194, v138
	v_exp_f32_e32 v180, v139
	v_exp_f32_e32 v196, v140
	v_exp_f32_e32 v190, v141
	v_exp_f32_e32 v198, v142
	v_exp_f32_e32 v184, v143
	v_cvt_pk_bf16_f32 v144, v173, v169
	v_cvt_pk_bf16_f32 v145, v177, v171
	v_cvt_pk_bf16_f32 v146, v183, v175
	v_cvt_pk_bf16_f32 v147, v189, v179
	v_cvt_pk_bf16_f32 v148, v193, v181
	v_cvt_pk_bf16_f32 v149, v195, v187
	v_cvt_pk_bf16_f32 v150, v197, v185
	v_cvt_pk_bf16_f32 v151, v199, v191
	v_cvt_pk_bf16_f32 v128, v172, v170
	v_cvt_pk_bf16_f32 v129, v176, v168
	v_cvt_pk_bf16_f32 v130, v182, v178
	v_cvt_pk_bf16_f32 v131, v188, v174
	v_cvt_pk_bf16_f32 v132, v192, v186
	v_cvt_pk_bf16_f32 v133, v194, v180
	v_cvt_pk_bf16_f32 v134, v196, v190
	v_cvt_pk_bf16_f32 v135, v198, v184
	v_add3_u32 v160, s99, v162, v160
	v_xad_u32 v252, v163, 64, s99
	v_add_u32_e32 v203, s99, v203
	v_add_u32_e32 v205, s99, v206
	ds_read_b64_tr_b16 v[136:137], v160 offset:32768
	ds_read_b64_tr_b16 v[138:139], v160 offset:34816
	ds_read_b64_tr_b16 v[140:141], v160 offset:36864
	ds_read_b64_tr_b16 v[142:143], v160 offset:38912
	ds_read_b64_tr_b16 v[152:153], v252 offset:32768
	ds_read_b64_tr_b16 v[154:155], v252 offset:34816
	ds_read_b64_tr_b16 v[156:157], v252 offset:36864
	ds_read_b64_tr_b16 v[158:159], v252 offset:38912
	ds_read_b64_tr_b16 v[208:209], v203 offset:32768
	ds_read_b64_tr_b16 v[210:211], v203 offset:34816
	ds_read_b64_tr_b16 v[212:213], v203 offset:36864
	ds_read_b64_tr_b16 v[214:215], v203 offset:38912
	ds_read_b64_tr_b16 v[216:217], v205 offset:32768
	ds_read_b64_tr_b16 v[218:219], v205 offset:34816
	ds_read_b64_tr_b16 v[220:221], v205 offset:36864
	ds_read_b64_tr_b16 v[222:223], v205 offset:38912
	s_waitcnt lgkmcnt(14)
	v_mfma_f32_32x32x16_bf16 v[64:79], v[144:147], v[136:139], v[64:79]
	v_mfma_f32_32x32x16_bf16 v[0:15], v[128:131], v[136:139], v[0:15]
	s_waitcnt lgkmcnt(10)
	v_mfma_f32_32x32x16_bf16 v[80:95], v[144:147], v[152:155], v[80:95]
	v_mfma_f32_32x32x16_bf16 v[16:31], v[128:131], v[152:155], v[16:31]
	s_waitcnt lgkmcnt(6)
	v_mfma_f32_32x32x16_bf16 v[96:111], v[144:147], v[208:211], v[96:111]
	v_mfma_f32_32x32x16_bf16 v[32:47], v[128:131], v[208:211], v[32:47]
	s_waitcnt lgkmcnt(2)
	v_mfma_f32_32x32x16_bf16 v[112:127], v[144:147], v[216:219], v[112:127]
	v_mfma_f32_32x32x16_bf16 v[48:63], v[128:131], v[216:219], v[48:63]
	v_mfma_f32_32x32x16_bf16 v[64:79], v[148:151], v[140:143], v[64:79]
	v_mfma_f32_32x32x16_bf16 v[0:15], v[132:135], v[140:143], v[0:15]
	v_mfma_f32_32x32x16_bf16 v[80:95], v[148:151], v[156:159], v[80:95]
	v_mfma_f32_32x32x16_bf16 v[16:31], v[132:135], v[156:159], v[16:31]
	v_mfma_f32_32x32x16_bf16 v[96:111], v[148:151], v[212:215], v[96:111]
	v_mfma_f32_32x32x16_bf16 v[32:47], v[132:135], v[212:215], v[32:47]
	s_waitcnt lgkmcnt(0)
	v_mfma_f32_32x32x16_bf16 v[112:127], v[148:151], v[220:223], v[112:127]
	v_mfma_f32_32x32x16_bf16 v[48:63], v[132:135], v[220:223], v[48:63]
	ds_read_b128 v[128:131], v207 offset:4096
	ds_read_b128 v[132:135], v224
	ds_read_b128 v[136:139], v225 offset:4096
	ds_read_b128 v[140:143], v226
	s_waitcnt lgkmcnt(2)
	v_mfma_f32_32x32x16_bf16 v[144:159], v[128:131], v[132:135], 0
	ds_read_b128 v[128:131], v227 offset:4096
	ds_read_b128 v[132:135], v228
	s_waitcnt lgkmcnt(2)
	v_mfma_f32_32x32x16_bf16 v[144:159], v[136:139], v[140:143], v[144:159]
	ds_read_b128 v[136:139], v230 offset:4096
	ds_read_b128 v[140:143], v232
	s_waitcnt lgkmcnt(2)
	v_mfma_f32_32x32x16_bf16 v[144:159], v[128:131], v[132:135], v[144:159]
	ds_read_b128 v[128:131], v207 offset:12288
	ds_read_b128 v[132:135], v224 offset:4096
	s_waitcnt lgkmcnt(2)
	v_mfma_f32_32x32x16_bf16 v[144:159], v[136:139], v[140:143], v[144:159]
	ds_read_b128 v[208:211], v225 offset:12288
	ds_read_b128 v[212:215], v226 offset:4096
	s_waitcnt lgkmcnt(2)
	v_mfma_f32_32x32x16_bf16 v[128:143], v[128:131], v[132:135], 0
	s_nop 7
	v_exp_f32_e32 v229, v144
	v_exp_f32_e32 v145, v145
	v_exp_f32_e32 v231, v146
	v_exp_f32_e32 v147, v147
	ds_read_b128 v[216:219], v227 offset:12288
	ds_read_b128 v[220:223], v228 offset:4096
	s_waitcnt lgkmcnt(2)
	v_mfma_f32_32x32x16_bf16 v[128:143], v[208:211], v[212:215], v[128:143]
	v_exp_f32_e32 v233, v148
	v_exp_f32_e32 v235, v149
	v_exp_f32_e32 v237, v150
	v_exp_f32_e32 v239, v151
	ds_read_b128 v[148:151], v230 offset:12288
	ds_read_b128 v[208:211], v232 offset:4096
	s_waitcnt lgkmcnt(2)
	v_mfma_f32_32x32x16_bf16 v[128:143], v[216:219], v[220:223], v[128:143]
	v_exp_f32_e32 v241, v152
	v_exp_f32_e32 v243, v153
	v_exp_f32_e32 v245, v154
	v_exp_f32_e32 v247, v155
	s_waitcnt lgkmcnt(0)
	v_mfma_f32_32x32x16_bf16 v[128:143], v[148:151], v[208:211], v[128:143]
	v_exp_f32_e32 v249, v156
	v_exp_f32_e32 v251, v157
	v_exp_f32_e32 v207, v158
	v_exp_f32_e32 v163, v159
	s_nop 7
	v_exp_f32_e32 v228, v128
	v_exp_f32_e32 v146, v129
	v_exp_f32_e32 v230, v130
	v_exp_f32_e32 v144, v131
	v_exp_f32_e32 v232, v132
	v_exp_f32_e32 v238, v133
	v_exp_f32_e32 v236, v134
	v_exp_f32_e32 v234, v135
	v_exp_f32_e32 v240, v136
	v_exp_f32_e32 v246, v137
	v_exp_f32_e32 v244, v138
	v_exp_f32_e32 v242, v139
	v_exp_f32_e32 v248, v140
	v_exp_f32_e32 v162, v141
	v_exp_f32_e32 v206, v142
	v_exp_f32_e32 v250, v143
	v_cvt_pk_bf16_f32 v148, v229, v145
	v_cvt_pk_bf16_f32 v149, v231, v147
	v_cvt_pk_bf16_f32 v150, v233, v235
	v_cvt_pk_bf16_f32 v151, v237, v239
	v_cvt_pk_bf16_f32 v152, v241, v243
	v_cvt_pk_bf16_f32 v153, v245, v247
	v_cvt_pk_bf16_f32 v154, v249, v251
	v_cvt_pk_bf16_f32 v155, v207, v163
	v_cvt_pk_bf16_f32 v128, v228, v146
	v_cvt_pk_bf16_f32 v129, v230, v144
	v_cvt_pk_bf16_f32 v130, v232, v238
	v_cvt_pk_bf16_f32 v131, v236, v234
	v_cvt_pk_bf16_f32 v132, v240, v246
	v_cvt_pk_bf16_f32 v133, v244, v242
	v_cvt_pk_bf16_f32 v134, v248, v162
	v_cvt_pk_bf16_f32 v135, v206, v250
	ds_read_b64_tr_b16 v[136:137], v160 offset:40960
	ds_read_b64_tr_b16 v[138:139], v160 offset:43008
	ds_read_b64_tr_b16 v[140:141], v160 offset:45056
	ds_read_b64_tr_b16 v[142:143], v160 offset:47104
	ds_read_b64_tr_b16 v[156:157], v252 offset:40960
	ds_read_b64_tr_b16 v[158:159], v252 offset:43008
	ds_read_b64_tr_b16 v[208:209], v252 offset:45056
	ds_read_b64_tr_b16 v[210:211], v252 offset:47104
	ds_read_b64_tr_b16 v[212:213], v203 offset:40960
	ds_read_b64_tr_b16 v[214:215], v203 offset:43008
	ds_read_b64_tr_b16 v[216:217], v203 offset:45056
	ds_read_b64_tr_b16 v[218:219], v203 offset:47104
	ds_read_b64_tr_b16 v[220:221], v205 offset:40960
	ds_read_b64_tr_b16 v[222:223], v205 offset:43008
	ds_read_b64_tr_b16 v[224:225], v205 offset:45056
	ds_read_b64_tr_b16 v[226:227], v205 offset:47104
	s_waitcnt lgkmcnt(14)
	v_mfma_f32_32x32x16_bf16 v[64:79], v[148:151], v[136:139], v[64:79]
	v_mfma_f32_32x32x16_bf16 v[0:15], v[128:131], v[136:139], v[0:15]
	s_waitcnt lgkmcnt(10)
	v_mfma_f32_32x32x16_bf16 v[80:95], v[148:151], v[156:159], v[80:95]
	v_mfma_f32_32x32x16_bf16 v[16:31], v[128:131], v[156:159], v[16:31]
	s_waitcnt lgkmcnt(6)
	v_mfma_f32_32x32x16_bf16 v[96:111], v[148:151], v[212:215], v[96:111]
	v_mfma_f32_32x32x16_bf16 v[32:47], v[128:131], v[212:215], v[32:47]
	s_waitcnt lgkmcnt(2)
	v_mfma_f32_32x32x16_bf16 v[112:127], v[148:151], v[220:223], v[112:127]
	v_mfma_f32_32x32x16_bf16 v[48:63], v[128:131], v[220:223], v[48:63]
	v_add_f32_e64 v128, v172, v176
	v_add_f32_e64 v129, v173, v177
	v_add_f32_e64 v130, v168, v170
	v_add_f32_e64 v131, v169, v171
	v_add_f32_e64 v128, v128, 0
	v_add_f32_e64 v129, v129, 0
	v_pk_add_f32 v[136:137], v[182:183], v[188:189]
	v_pk_add_f32 v[130:131], v[130:131], 0 op_sel_hi:[1,0]
	v_pk_add_f32 v[128:129], v[136:137], v[128:129]
	v_pk_add_f32 v[136:137], v[174:175], v[178:179]
	v_pk_add_f32 v[138:139], v[232:233], v[236:237]
	v_pk_add_f32 v[130:131], v[136:137], v[130:131]
	v_pk_add_f32 v[136:137], v[192:193], v[194:195]
	v_mfma_f32_32x32x16_bf16 v[64:79], v[152:155], v[140:143], v[64:79]
	v_add_f32_e64 v128, v136, v128
	v_add_f32_e64 v129, v137, v129
	v_add_f32_e64 v136, v180, v186
	v_add_f32_e64 v137, v181, v187
	v_add_f32_e64 v130, v136, v130
	v_add_f32_e64 v131, v137, v131
	v_pk_add_f32 v[136:137], v[196:197], v[198:199]
	s_nop 0
	v_pk_add_f32 v[128:129], v[136:137], v[128:129]
	v_pk_add_f32 v[136:137], v[184:185], v[190:191]
	v_mfma_f32_32x32x16_bf16 v[0:15], v[132:135], v[140:143], v[0:15]
	v_add_f32_e64 v130, v136, v130
	v_add_f32_e64 v131, v137, v131
	v_add_f32_e64 v136, v144, v146
	v_add_f32_e64 v137, v145, v147
	v_add_f32_e64 v128, v128, v130
	v_add_f32_e64 v129, v129, v131
	v_pk_add_f32 v[130:131], v[228:229], v[230:231]
	v_pk_add_f32 v[136:137], v[136:137], 0 op_sel_hi:[1,0]
	v_pk_add_f32 v[130:131], v[130:131], 0 op_sel_hi:[1,0]
	v_pk_add_f32 v[128:129], v[166:167], v[128:129]
	v_mfma_f32_32x32x16_bf16 v[80:95], v[152:155], v[208:211], v[80:95]
	v_add_f32_e64 v130, v138, v130
	v_add_f32_e64 v131, v139, v131
	v_add_f32_e64 v138, v234, v238
	v_add_f32_e64 v139, v235, v239
	v_add_f32_e64 v136, v138, v136
	v_add_f32_e64 v137, v139, v137
	v_pk_add_f32 v[138:139], v[240:241], v[244:245]
	s_nop 0
	v_pk_add_f32 v[130:131], v[138:139], v[130:131]
	v_mfma_f32_32x32x16_bf16 v[16:31], v[132:135], v[208:211], v[16:31]
	v_add_f32_e64 v138, v242, v246
	v_add_f32_e64 v139, v243, v247
	v_add_f32_e64 v136, v138, v136
	v_add_f32_e64 v137, v139, v137
	v_add_f32_e64 v138, v248, v206
	v_add_f32_e64 v139, v249, v207
	v_pk_add_f32 v[130:131], v[138:139], v[130:131]
	v_pk_add_f32 v[138:139], v[250:251], v[162:163]
	v_mfma_f32_32x32x16_bf16 v[96:111], v[152:155], v[216:219], v[96:111]
	v_add_f32_e64 v136, v138, v136
	v_add_f32_e64 v137, v139, v137
	v_add_f32_e64 v130, v130, v136
	v_add_f32_e64 v131, v131, v137
	v_add_f32_e64 v166, v128, v130
	v_add_f32_e64 v167, v129, v131
	v_mfma_f32_32x32x16_bf16 v[32:47], v[132:135], v[216:219], v[32:47]
	s_waitcnt lgkmcnt(0)
	v_mfma_f32_32x32x16_bf16 v[112:127], v[152:155], v[224:227], v[112:127]
	v_mfma_f32_32x32x16_bf16 v[48:63], v[132:135], v[224:227], v[48:63]
	s_waitcnt vmcnt(0)
	s_waitcnt lgkmcnt(0)
	s_addk_i32 s5, 0x4000
	s_add_i32 s4, s4, 0x10000
	s_mov_b32 s98, s99
	s_mov_b32 s99, s100
	s_mov_b32 s100, s101
	s_mov_b32 s101, s98
	s_cmp_eq_u32 s4, 0x400000
	s_barrier
	s_cbranch_scc1 .LBB0_410
.LBB0_408:
	s_cmp_eq_u32 s4, 0x3f0000
	s_movk_i32 s7, 0x4000
	s_cbranch_scc1 .LBB0_407
	s_and_b32 s7, s5, 0x4000
	s_branch .LBB0_407
.Lattn_late_entry:
	s_cmp_eq_u32 s4, 0x3f0000
	s_movk_i32 s7, 0x4000
	s_cbranch_scc1 .Lattn_late_h_e
	s_and_b32 s7, s5, 0x4000
.Lattn_late_h_e:
	s_branch .Lattn_late_mid

.Lattn_late_h_l:
	ds_read_b64_tr_b16 v[136:137], v160 offset:40960
	ds_read_b64_tr_b16 v[138:139], v160 offset:43008
	ds_read_b64_tr_b16 v[140:141], v160 offset:45056
	ds_read_b64_tr_b16 v[142:143], v160 offset:47104
	ds_read_b64_tr_b16 v[156:157], v252 offset:40960
	ds_read_b64_tr_b16 v[158:159], v252 offset:43008
	ds_read_b64_tr_b16 v[208:209], v252 offset:45056
	ds_read_b64_tr_b16 v[210:211], v252 offset:47104
	ds_read_b64_tr_b16 v[212:213], v203 offset:40960
	ds_read_b64_tr_b16 v[214:215], v203 offset:43008
	ds_read_b64_tr_b16 v[216:217], v203 offset:45056
	ds_read_b64_tr_b16 v[218:219], v203 offset:47104
	ds_read_b64_tr_b16 v[220:221], v205 offset:40960
	ds_read_b64_tr_b16 v[222:223], v205 offset:43008
	ds_read_b64_tr_b16 v[224:225], v205 offset:45056
	ds_read_b64_tr_b16 v[226:227], v205 offset:47104
	s_waitcnt lgkmcnt(14)
	v_mfma_f32_32x32x16_bf16 v[64:79], v[148:151], v[136:139], v[64:79]
	v_mfma_f32_32x32x16_bf16 v[0:15], v[128:131], v[136:139], v[0:15]
	s_waitcnt lgkmcnt(10)
	v_mfma_f32_32x32x16_bf16 v[80:95], v[148:151], v[156:159], v[80:95]
	v_mfma_f32_32x32x16_bf16 v[16:31], v[128:131], v[156:159], v[16:31]
	s_waitcnt lgkmcnt(6)
	v_mfma_f32_32x32x16_bf16 v[96:111], v[148:151], v[212:215], v[96:111]
	v_mfma_f32_32x32x16_bf16 v[32:47], v[128:131], v[212:215], v[32:47]
	s_waitcnt lgkmcnt(2)
	v_mfma_f32_32x32x16_bf16 v[112:127], v[148:151], v[220:223], v[112:127]
	v_mfma_f32_32x32x16_bf16 v[48:63], v[128:131], v[220:223], v[48:63]
	v_add_f32_e64 v128, v172, v176
	v_add_f32_e64 v129, v173, v177
	v_add_f32_e64 v130, v168, v170
	v_add_f32_e64 v131, v169, v171
	v_add_f32_e64 v128, v128, 0
	v_add_f32_e64 v129, v129, 0
	v_pk_add_f32 v[136:137], v[182:183], v[188:189]
	v_pk_add_f32 v[130:131], v[130:131], 0 op_sel_hi:[1,0]
	v_pk_add_f32 v[128:129], v[136:137], v[128:129]
	v_pk_add_f32 v[136:137], v[174:175], v[178:179]
	v_pk_add_f32 v[138:139], v[232:233], v[236:237]
	v_pk_add_f32 v[130:131], v[136:137], v[130:131]
	v_pk_add_f32 v[136:137], v[192:193], v[194:195]
	v_mfma_f32_32x32x16_bf16 v[64:79], v[152:155], v[140:143], v[64:79]
	v_add_f32_e64 v128, v136, v128
	v_add_f32_e64 v129, v137, v129
	v_add_f32_e64 v136, v180, v186
	v_add_f32_e64 v137, v181, v187
	v_add_f32_e64 v130, v136, v130
	v_add_f32_e64 v131, v137, v131
	v_pk_add_f32 v[136:137], v[196:197], v[198:199]
	s_nop 0
	v_pk_add_f32 v[128:129], v[136:137], v[128:129]
	v_pk_add_f32 v[136:137], v[184:185], v[190:191]
	v_mfma_f32_32x32x16_bf16 v[0:15], v[132:135], v[140:143], v[0:15]
	v_add_f32_e64 v130, v136, v130
	v_add_f32_e64 v131, v137, v131
	v_add_f32_e64 v136, v144, v146
	v_add_f32_e64 v137, v145, v147
	v_add_f32_e64 v128, v128, v130
	v_add_f32_e64 v129, v129, v131
	v_pk_add_f32 v[130:131], v[228:229], v[230:231]
	v_pk_add_f32 v[136:137], v[136:137], 0 op_sel_hi:[1,0]
	v_pk_add_f32 v[130:131], v[130:131], 0 op_sel_hi:[1,0]
	v_pk_add_f32 v[128:129], v[166:167], v[128:129]
	v_mfma_f32_32x32x16_bf16 v[80:95], v[152:155], v[208:211], v[80:95]
	v_add_f32_e64 v130, v138, v130
	v_add_f32_e64 v131, v139, v131
	v_add_f32_e64 v138, v234, v238
	v_add_f32_e64 v139, v235, v239
	v_add_f32_e64 v136, v138, v136
	v_add_f32_e64 v137, v139, v137
	v_pk_add_f32 v[138:139], v[240:241], v[244:245]
	s_nop 0
	v_pk_add_f32 v[130:131], v[138:139], v[130:131]
	v_mfma_f32_32x32x16_bf16 v[16:31], v[132:135], v[208:211], v[16:31]
	v_add_f32_e64 v138, v242, v246
	v_add_f32_e64 v139, v243, v247
	v_add_f32_e64 v136, v138, v136
	v_add_f32_e64 v137, v139, v137
	v_add_f32_e64 v138, v248, v206
	v_add_f32_e64 v139, v249, v207
	v_pk_add_f32 v[130:131], v[138:139], v[130:131]
	v_pk_add_f32 v[138:139], v[250:251], v[162:163]
	v_mfma_f32_32x32x16_bf16 v[96:111], v[152:155], v[216:219], v[96:111]
	v_add_f32_e64 v136, v138, v136
	v_add_f32_e64 v137, v139, v137
	v_add_f32_e64 v130, v130, v136
	v_add_f32_e64 v131, v131, v137
	v_add_f32_e64 v166, v128, v130
	v_add_f32_e64 v167, v129, v131
	v_mfma_f32_32x32x16_bf16 v[32:47], v[132:135], v[216:219], v[32:47]
	s_waitcnt lgkmcnt(0)
	v_mfma_f32_32x32x16_bf16 v[112:127], v[152:155], v[224:227], v[112:127]
	v_mfma_f32_32x32x16_bf16 v[48:63], v[132:135], v[224:227], v[48:63]

.Lattn_dma_done_l:
	v_exp_f32_e32 v172, v128
	v_exp_f32_e32 v170, v129
	v_exp_f32_e32 v176, v130
	v_exp_f32_e32 v168, v131
	v_exp_f32_e32 v182, v132
	v_exp_f32_e32 v178, v133
	v_exp_f32_e32 v188, v134
	v_exp_f32_e32 v174, v135
	v_exp_f32_e32 v192, v136
	v_exp_f32_e32 v186, v137
	v_exp_f32_e32 v194, v138
	v_exp_f32_e32 v180, v139
	v_exp_f32_e32 v196, v140
	v_exp_f32_e32 v190, v141
	v_exp_f32_e32 v198, v142
	v_exp_f32_e32 v184, v143
	v_cvt_pk_bf16_f32 v144, v173, v169
	v_cvt_pk_bf16_f32 v145, v177, v171
	v_cvt_pk_bf16_f32 v146, v183, v175
	v_cvt_pk_bf16_f32 v147, v189, v179
	v_cvt_pk_bf16_f32 v148, v193, v181
	v_cvt_pk_bf16_f32 v149, v195, v187
	v_cvt_pk_bf16_f32 v150, v197, v185
	v_cvt_pk_bf16_f32 v151, v199, v191
	v_cvt_pk_bf16_f32 v128, v172, v170
	v_cvt_pk_bf16_f32 v129, v176, v168
	v_cvt_pk_bf16_f32 v130, v182, v178
	v_cvt_pk_bf16_f32 v131, v188, v174
	v_cvt_pk_bf16_f32 v132, v192, v186
	v_cvt_pk_bf16_f32 v133, v194, v180
	v_cvt_pk_bf16_f32 v134, v196, v190
	v_cvt_pk_bf16_f32 v135, v198, v184
	v_add3_u32 v160, s99, v162, v160
	v_xad_u32 v252, v163, 64, s99
	v_add_u32_e32 v203, s99, v203
	v_add_u32_e32 v205, s99, v206
	ds_read_b64_tr_b16 v[136:137], v160 offset:32768
	ds_read_b64_tr_b16 v[138:139], v160 offset:34816
	ds_read_b64_tr_b16 v[140:141], v160 offset:36864
	ds_read_b64_tr_b16 v[142:143], v160 offset:38912
	ds_read_b64_tr_b16 v[152:153], v252 offset:32768
	ds_read_b64_tr_b16 v[154:155], v252 offset:34816
	ds_read_b64_tr_b16 v[156:157], v252 offset:36864
	ds_read_b64_tr_b16 v[158:159], v252 offset:38912
	ds_read_b64_tr_b16 v[208:209], v203 offset:32768
	ds_read_b64_tr_b16 v[210:211], v203 offset:34816
	ds_read_b64_tr_b16 v[212:213], v203 offset:36864
	ds_read_b64_tr_b16 v[214:215], v203 offset:38912
	ds_read_b64_tr_b16 v[216:217], v205 offset:32768
	ds_read_b64_tr_b16 v[218:219], v205 offset:34816
	ds_read_b64_tr_b16 v[220:221], v205 offset:36864
	ds_read_b64_tr_b16 v[222:223], v205 offset:38912
	s_waitcnt lgkmcnt(14)
	v_mfma_f32_32x32x16_bf16 v[64:79], v[144:147], v[136:139], v[64:79]
	v_mfma_f32_32x32x16_bf16 v[0:15], v[128:131], v[136:139], v[0:15]
	s_waitcnt lgkmcnt(10)
	v_mfma_f32_32x32x16_bf16 v[80:95], v[144:147], v[152:155], v[80:95]
	v_mfma_f32_32x32x16_bf16 v[16:31], v[128:131], v[152:155], v[16:31]
	s_waitcnt lgkmcnt(6)
	v_mfma_f32_32x32x16_bf16 v[96:111], v[144:147], v[208:211], v[96:111]
	v_mfma_f32_32x32x16_bf16 v[32:47], v[128:131], v[208:211], v[32:47]
	s_waitcnt lgkmcnt(2)
	v_mfma_f32_32x32x16_bf16 v[112:127], v[144:147], v[216:219], v[112:127]
	v_mfma_f32_32x32x16_bf16 v[48:63], v[128:131], v[216:219], v[48:63]
	v_mfma_f32_32x32x16_bf16 v[64:79], v[148:151], v[140:143], v[64:79]
	v_mfma_f32_32x32x16_bf16 v[0:15], v[132:135], v[140:143], v[0:15]
	v_mfma_f32_32x32x16_bf16 v[80:95], v[148:151], v[156:159], v[80:95]
	v_mfma_f32_32x32x16_bf16 v[16:31], v[132:135], v[156:159], v[16:31]
	v_mfma_f32_32x32x16_bf16 v[96:111], v[148:151], v[212:215], v[96:111]
	v_mfma_f32_32x32x16_bf16 v[32:47], v[132:135], v[212:215], v[32:47]
	s_waitcnt lgkmcnt(0)
	v_mfma_f32_32x32x16_bf16 v[112:127], v[148:151], v[220:223], v[112:127]
	v_mfma_f32_32x32x16_bf16 v[48:63], v[132:135], v[220:223], v[48:63]
	ds_read_b128 v[128:131], v207 offset:4096
	ds_read_b128 v[132:135], v224
	ds_read_b128 v[136:139], v225 offset:4096
	ds_read_b128 v[140:143], v226
	s_waitcnt lgkmcnt(2)
	v_mfma_f32_32x32x16_bf16 v[144:159], v[128:131], v[132:135], 0
	ds_read_b128 v[128:131], v227 offset:4096
	ds_read_b128 v[132:135], v228
	s_waitcnt lgkmcnt(2)
	v_mfma_f32_32x32x16_bf16 v[144:159], v[136:139], v[140:143], v[144:159]
	ds_read_b128 v[136:139], v230 offset:4096
	ds_read_b128 v[140:143], v232
	s_waitcnt lgkmcnt(2)
	v_mfma_f32_32x32x16_bf16 v[144:159], v[128:131], v[132:135], v[144:159]
	ds_read_b128 v[128:131], v207 offset:12288
	ds_read_b128 v[132:135], v224 offset:4096
	s_waitcnt lgkmcnt(2)
	v_mfma_f32_32x32x16_bf16 v[144:159], v[136:139], v[140:143], v[144:159]
	ds_read_b128 v[208:211], v225 offset:12288
	ds_read_b128 v[212:215], v226 offset:4096
	s_waitcnt lgkmcnt(2)
	v_mfma_f32_32x32x16_bf16 v[128:143], v[128:131], v[132:135], 0
	s_nop 7
	v_exp_f32_e32 v229, v144
	v_exp_f32_e32 v145, v145
	v_exp_f32_e32 v231, v146
	v_exp_f32_e32 v147, v147
	ds_read_b128 v[216:219], v227 offset:12288
	ds_read_b128 v[220:223], v228 offset:4096
	s_waitcnt lgkmcnt(2)
	v_mfma_f32_32x32x16_bf16 v[128:143], v[208:211], v[212:215], v[128:143]
	v_exp_f32_e32 v233, v148
	v_exp_f32_e32 v235, v149
	v_exp_f32_e32 v237, v150
	v_exp_f32_e32 v239, v151
	ds_read_b128 v[148:151], v230 offset:12288
	ds_read_b128 v[208:211], v232 offset:4096
	s_waitcnt lgkmcnt(2)
	v_mfma_f32_32x32x16_bf16 v[128:143], v[216:219], v[220:223], v[128:143]
	v_exp_f32_e32 v241, v152
	v_exp_f32_e32 v243, v153
	v_exp_f32_e32 v245, v154
	v_exp_f32_e32 v247, v155
	s_waitcnt lgkmcnt(0)
	v_mfma_f32_32x32x16_bf16 v[128:143], v[148:151], v[208:211], v[128:143]
	v_exp_f32_e32 v249, v156
	v_exp_f32_e32 v251, v157
	v_exp_f32_e32 v207, v158
	v_exp_f32_e32 v163, v159
	s_nop 7
	v_exp_f32_e32 v228, v128
	v_exp_f32_e32 v146, v129
	v_exp_f32_e32 v230, v130
	v_exp_f32_e32 v144, v131
	v_exp_f32_e32 v232, v132
	v_exp_f32_e32 v238, v133
	v_exp_f32_e32 v236, v134
	v_exp_f32_e32 v234, v135
	v_exp_f32_e32 v240, v136
	v_exp_f32_e32 v246, v137
	v_exp_f32_e32 v244, v138
	v_exp_f32_e32 v242, v139
	v_exp_f32_e32 v248, v140
	v_exp_f32_e32 v162, v141
	v_exp_f32_e32 v206, v142
	v_exp_f32_e32 v250, v143
	v_cvt_pk_bf16_f32 v148, v229, v145
	v_cvt_pk_bf16_f32 v149, v231, v147
	v_cvt_pk_bf16_f32 v150, v233, v235
	v_cvt_pk_bf16_f32 v151, v237, v239
	v_cvt_pk_bf16_f32 v152, v241, v243
	v_cvt_pk_bf16_f32 v153, v245, v247
	v_cvt_pk_bf16_f32 v154, v249, v251
	v_cvt_pk_bf16_f32 v155, v207, v163
	v_cvt_pk_bf16_f32 v128, v228, v146
	v_cvt_pk_bf16_f32 v129, v230, v144
	v_cvt_pk_bf16_f32 v130, v232, v238
	v_cvt_pk_bf16_f32 v131, v236, v234
	v_cvt_pk_bf16_f32 v132, v240, v246
	v_cvt_pk_bf16_f32 v133, v244, v242
	v_cvt_pk_bf16_f32 v134, v248, v162
	v_cvt_pk_bf16_f32 v135, v206, v250
	s_waitcnt vmcnt(0)
	s_waitcnt lgkmcnt(0)
	s_addk_i32 s5, 0x4000
	s_add_i32 s4, s4, 0x10000
	s_mov_b32 s98, s99
	s_mov_b32 s99, s100
	s_mov_b32 s100, s101
	s_mov_b32 s101, s98
	s_cmp_eq_u32 s4, 0x400000
	s_barrier
	s_cbranch_scc0 .Lattn_late_loop
	ds_read_b64_tr_b16 v[136:137], v160 offset:40960
	ds_read_b64_tr_b16 v[138:139], v160 offset:43008
	ds_read_b64_tr_b16 v[140:141], v160 offset:45056
	ds_read_b64_tr_b16 v[142:143], v160 offset:47104
	ds_read_b64_tr_b16 v[156:157], v252 offset:40960
	ds_read_b64_tr_b16 v[158:159], v252 offset:43008
	ds_read_b64_tr_b16 v[208:209], v252 offset:45056
	ds_read_b64_tr_b16 v[210:211], v252 offset:47104
	ds_read_b64_tr_b16 v[212:213], v203 offset:40960
	ds_read_b64_tr_b16 v[214:215], v203 offset:43008
	ds_read_b64_tr_b16 v[216:217], v203 offset:45056
	ds_read_b64_tr_b16 v[218:219], v203 offset:47104
	ds_read_b64_tr_b16 v[220:221], v205 offset:40960
	ds_read_b64_tr_b16 v[222:223], v205 offset:43008
	ds_read_b64_tr_b16 v[224:225], v205 offset:45056
	ds_read_b64_tr_b16 v[226:227], v205 offset:47104
	s_waitcnt lgkmcnt(14)
	v_mfma_f32_32x32x16_bf16 v[64:79], v[148:151], v[136:139], v[64:79]
	v_mfma_f32_32x32x16_bf16 v[0:15], v[128:131], v[136:139], v[0:15]
	s_waitcnt lgkmcnt(10)
	v_mfma_f32_32x32x16_bf16 v[80:95], v[148:151], v[156:159], v[80:95]
	v_mfma_f32_32x32x16_bf16 v[16:31], v[128:131], v[156:159], v[16:31]
	s_waitcnt lgkmcnt(6)
	v_mfma_f32_32x32x16_bf16 v[96:111], v[148:151], v[212:215], v[96:111]
	v_mfma_f32_32x32x16_bf16 v[32:47], v[128:131], v[212:215], v[32:47]
	s_waitcnt lgkmcnt(2)
	v_mfma_f32_32x32x16_bf16 v[112:127], v[148:151], v[220:223], v[112:127]
	v_mfma_f32_32x32x16_bf16 v[48:63], v[128:131], v[220:223], v[48:63]
	v_add_f32_e64 v128, v172, v176
	v_add_f32_e64 v129, v173, v177
	v_add_f32_e64 v130, v168, v170
	v_add_f32_e64 v131, v169, v171
	v_add_f32_e64 v128, v128, 0
	v_add_f32_e64 v129, v129, 0
	v_pk_add_f32 v[136:137], v[182:183], v[188:189]
	v_pk_add_f32 v[130:131], v[130:131], 0 op_sel_hi:[1,0]
	v_pk_add_f32 v[128:129], v[136:137], v[128:129]
	v_pk_add_f32 v[136:137], v[174:175], v[178:179]
	v_pk_add_f32 v[138:139], v[232:233], v[236:237]
	v_pk_add_f32 v[130:131], v[136:137], v[130:131]
	v_pk_add_f32 v[136:137], v[192:193], v[194:195]
	v_mfma_f32_32x32x16_bf16 v[64:79], v[152:155], v[140:143], v[64:79]
	v_add_f32_e64 v128, v136, v128
	v_add_f32_e64 v129, v137, v129
	v_add_f32_e64 v136, v180, v186
	v_add_f32_e64 v137, v181, v187
	v_add_f32_e64 v130, v136, v130
	v_add_f32_e64 v131, v137, v131
	v_pk_add_f32 v[136:137], v[196:197], v[198:199]
	s_nop 0
	v_pk_add_f32 v[128:129], v[136:137], v[128:129]
	v_pk_add_f32 v[136:137], v[184:185], v[190:191]
	v_mfma_f32_32x32x16_bf16 v[0:15], v[132:135], v[140:143], v[0:15]
	v_add_f32_e64 v130, v136, v130
	v_add_f32_e64 v131, v137, v131
	v_add_f32_e64 v136, v144, v146
	v_add_f32_e64 v137, v145, v147
	v_add_f32_e64 v128, v128, v130
	v_add_f32_e64 v129, v129, v131
	v_pk_add_f32 v[130:131], v[228:229], v[230:231]
	v_pk_add_f32 v[136:137], v[136:137], 0 op_sel_hi:[1,0]
	v_pk_add_f32 v[130:131], v[130:131], 0 op_sel_hi:[1,0]
	v_pk_add_f32 v[128:129], v[166:167], v[128:129]
	v_mfma_f32_32x32x16_bf16 v[80:95], v[152:155], v[208:211], v[80:95]
	v_add_f32_e64 v130, v138, v130
	v_add_f32_e64 v131, v139, v131
	v_add_f32_e64 v138, v234, v238
	v_add_f32_e64 v139, v235, v239
	v_add_f32_e64 v136, v138, v136
	v_add_f32_e64 v137, v139, v137
	v_pk_add_f32 v[138:139], v[240:241], v[244:245]
	s_nop 0
	v_pk_add_f32 v[130:131], v[138:139], v[130:131]
	v_mfma_f32_32x32x16_bf16 v[16:31], v[132:135], v[208:211], v[16:31]
	v_add_f32_e64 v138, v242, v246
	v_add_f32_e64 v139, v243, v247
	v_add_f32_e64 v136, v138, v136
	v_add_f32_e64 v137, v139, v137
	v_add_f32_e64 v138, v248, v206
	v_add_f32_e64 v139, v249, v207
	v_pk_add_f32 v[130:131], v[138:139], v[130:131]
	v_pk_add_f32 v[138:139], v[250:251], v[162:163]
	v_mfma_f32_32x32x16_bf16 v[96:111], v[152:155], v[216:219], v[96:111]
	v_add_f32_e64 v136, v138, v136
	v_add_f32_e64 v137, v139, v137
	v_add_f32_e64 v130, v130, v136
	v_add_f32_e64 v131, v131, v137
	v_add_f32_e64 v166, v128, v130
	v_add_f32_e64 v167, v129, v131
	v_mfma_f32_32x32x16_bf16 v[32:47], v[132:135], v[216:219], v[32:47]
	s_waitcnt lgkmcnt(0)
	v_mfma_f32_32x32x16_bf16 v[112:127], v[152:155], v[224:227], v[112:127]
	v_mfma_f32_32x32x16_bf16 v[48:63], v[132:135], v[224:227], v[48:63]
	s_nop 7
	s_nop 3
	s_branch .LBB0_410
